# deferred weight conversion into idle HGRN-phase workgroups; memory-attention units grabbed two per atomic
# speedup vs baseline: 1.0551x; 1.0051x over previous
.LBB0_82:
	v_mov_b32_e32 v1, v186
	v_readlane_b32 s0, v243, 28
	v_ashrrev_i32_e32 v1, 6, v1
	s_mov_b64 s[10:11], 0
	s_mov_b32 s60, 0
	s_waitcnt lgkmcnt(0)
	v_add_u32_e32 v3, s0, v1
	s_branch .LBB0_85

.LBB0_85:
	v_readlane_b32 s2, v240, 15
	v_readlane_b32 s3, v240, 16
	s_mov_b64 s[0:1], -1
	s_and_b64 vcc, exec, s[2:3]
	s_cbranch_vccz .LBB0_91
	s_cmp_lg_u32 s60, 0
	s_cbranch_scc1 .Lmemb_have
	v_mov_b32_e32 v1, v186
	s_nop 0
	v_and_b32_e32 v2, 63, v1
	v_mov_b32_e32 v1, 0
	v_cmp_eq_u32_e32 vcc, 0, v2
	s_and_saveexec_b64 s[0:1], vcc
	s_cbranch_execz .LBB0_90
	s_mov_b64 s[4:5], exec
	v_mbcnt_lo_u32_b32 v1, s4, 0
	v_mbcnt_hi_u32_b32 v1, s5, v1
	v_cmp_eq_u32_e32 vcc, 0, v1
	s_and_saveexec_b64 s[2:3], vcc
	s_cbranch_execz .LBB0_89
	s_bcnt1_i32_b64 s4, s[4:5]
	s_lshl_b32 s4, s4, 1
	v_mov_b32_e32 v2, s4
	v_readlane_b32 s4, v240, 22
	v_readlane_b32 s5, v240, 23
	s_nop 4
	global_atomic_add v2, v0, v2, s[4:5] sc0

.LBB0_90:
	s_or_b64 exec, exec, s[0:1]
	v_readfirstlane_b32 s3, v1
	s_nop 0
	s_mov_b32 s61, s3
	s_mov_b32 s60, 2
.Lmemb_have:
	s_mov_b32 s3, s61
	s_add_i32 s61, s61, 1
	s_add_i32 s60, s60, -1
	s_mov_b64 s[0:1], 0

.LBB0_181:
	v_readlane_b32 s0, v240, 14
	s_cmp_lg_u32 s0, 0
	s_cbranch_scc1 .Lmixa_nodefer
	v_readlane_b32 s2, v243, 42
	v_readlane_b32 s3, v243, 43
	v_readlane_b32 s4, v240, 17
	v_readlane_b32 s5, v240, 18
	s_or_b64 s[2:3], s[2:3], s[4:5]
	v_readlane_b32 s4, v243, 12
	v_readlane_b32 s5, v243, 13
	s_or_b64 s[2:3], s[2:3], s[4:5]
	s_and_b64 vcc, exec, s[2:3]
	s_cbranch_vccnz .Lmixa_nodefer
	v_readlane_b32 s90, v241, 25
	v_readlane_b32 s91, v241, 1
	s_nop 0
	s_sub_i32 s0, s90, 96
	s_sub_i32 s1, s91, 0x78
	v_writelane_b32 v241, s1, 1
	s_lshl_b32 s2, s0, 6
	v_writelane_b32 v241, s2, 2
	v_writelane_b32 v241, s2, 5
	s_lshl_b32 s2, s1, 6
	v_writelane_b32 v241, s2, 7
	s_lshl_b32 s2, s0, 7
	v_writelane_b32 v241, s2, 9
	s_lshl_b32 s2, s0, 5
	v_writelane_b32 v241, s2, 10
	v_writelane_b32 v241, s0, 25
	s_mov_b32 s96, 0x1ddc1c
	s_movk_i32 s33, 0x300
	s_movk_i32 s44, 0x100
	s_movk_i32 s45, 0x90
	s_movk_i32 s0, 0xff72
	s_waitcnt vmcnt(0) lgkmcnt(0)
	s_barrier
	v_mov_b32_e32 v4, v186
	s_mov_b32 s20, 0
	v_ashrrev_i32_e32 v1, 3, v4
	v_lshlrev_b32_e32 v2, 3, v4
	v_and_b32_e32 v10, 56, v2
	v_mul_lo_u32 v2, v1, s45
	v_add_u32_e32 v2, 0, v2
	v_lshl_add_u32 v11, v10, 1, v2
	s_waitcnt lgkmcnt(0)
	v_mad_u64_u32 v[2:3], s[0:1], v1, s0, v[2:3]
	v_mul_u32_u24_e32 v3, 0x90, v10
	v_and_b32_e32 v4, 7, v4
	v_readlane_b32 s0, v241, 9
	v_add_u32_e32 v17, v2, v3
	s_nop 0
	v_lshl_add_u32 v16, v4, 4, s0
	s_branch .Lpw_978

.Lpw_978:
	s_bitcmp1_b32 s96, s20
	s_cbranch_scc0 .Lpw_977
	s_mul_i32 s0, s20, 40
	v_readlane_b32 s2, v243, 2
	s_mul_hi_u32 s1, s20, 40
	v_readlane_b32 s3, v243, 3
	s_add_u32 s0, s2, s0
	s_addc_u32 s1, s3, s1
	s_load_dwordx4 s[8:11], s[0:1], 0x108
	s_waitcnt lgkmcnt(0)
	s_ashr_i32 s4, s10, 6
	s_ashr_i32 s2, s8, 6
	s_mul_i32 s10, s4, s2
	v_readlane_b32 s2, v241, 25
	s_cmp_ge_i32 s2, s10
	v_readlane_b32 s3, v241, 26
	s_cbranch_scc1 .Lpw_977
	s_load_dwordx4 s[12:15], s[0:1], 0xf0
	s_nop 0
	s_load_dwordx2 s[0:1], s[0:1], 0x100
	v_readlane_b32 s18, v241, 1
	s_mov_b32 s21, s9
	v_readlane_b32 s31, v241, 10
	s_waitcnt lgkmcnt(0)
	s_cmp_lg_u64 s[14:15], 0
	s_cselect_b64 s[2:3], -1, 0
	s_abs_i32 s23, s4
	v_cvt_f32_u32_e32 v2, s23
	s_ashr_i32 s22, s4, 31
	s_lshl_b32 s5, s4, 6
	s_lshl_b32 s16, s4, 7
	v_rcp_iflag_f32_e32 v2, v2
	s_sub_i32 s25, 0, s4
	s_lshl_b32 s4, s4, 5
	s_sub_i32 s17, 0, s23
	v_mul_f32_e32 v2, 0x4f7ffffe, v2
	v_cvt_u32_f32_e32 v2, v2
	s_sub_i32 s28, 0, s4
	s_sub_i32 s26, 0, s5
	s_lshl_b32 s24, s18, 7
	v_readfirstlane_b32 s4, v2
	s_mul_i32 s17, s17, s4
	s_mul_hi_u32 s5, s4, s17
	s_add_i32 s29, s4, s5
	v_readlane_b32 s4, v241, 25
	s_sub_i32 s27, 0, s16
	s_lshl_b32 s30, s18, 5
	v_mov_b32_e32 v18, v16
	v_readlane_b32 s34, v241, 5
	s_mov_b32 s35, s4
	v_readlane_b32 s19, v241, 2
	v_readlane_b32 s5, v241, 26
	s_branch .Lpw_982

.Lprep_deferred_ret:
	s_waitcnt vmcnt(0) lgkmcnt(0)
	s_barrier
	v_writelane_b32 v241, s91, 1
	s_lshl_b32 s2, s90, 6
	v_writelane_b32 v241, s2, 2
	v_writelane_b32 v241, s2, 5
	s_lshl_b32 s2, s91, 6
	v_writelane_b32 v241, s2, 7
	s_lshl_b32 s2, s90, 7
	v_writelane_b32 v241, s2, 9
	s_lshl_b32 s2, s90, 5
	v_writelane_b32 v241, s2, 10
	v_writelane_b32 v241, s90, 25
	s_nop 1

.LBB0_975:
	s_and_b64 vcc, exec, s[0:1]
	s_movk_i32 s0, 0xff72
	s_cbranch_vccz .LBB0_1057
	s_mov_b32 s96, 0x223e3
	v_mov_b32_e32 v4, v186
	s_mov_b32 s20, 0
	v_ashrrev_i32_e32 v1, 3, v4
	v_lshlrev_b32_e32 v2, 3, v4
	v_and_b32_e32 v10, 56, v2
	v_mul_lo_u32 v2, v1, s45
	v_add_u32_e32 v2, 0, v2
	v_lshl_add_u32 v11, v10, 1, v2
	s_waitcnt lgkmcnt(0)
	v_mad_u64_u32 v[2:3], s[0:1], v1, s0, v[2:3]
	v_mul_u32_u24_e32 v3, 0x90, v10
	v_and_b32_e32 v4, 7, v4
	v_readlane_b32 s0, v241, 9
	v_add_u32_e32 v17, v2, v3
	s_nop 0
	v_lshl_add_u32 v16, v4, 4, s0
	s_branch .LBB0_978
